# HGRN2 core: state-update MFMAs with swapped operands so the bf16 state image is written with 2 ds_write_b64 instead of 8 ds_write_b16 per chunk, per-key-dim decay read as 2 ds_read_b128, 7 accumulator
# speedup vs baseline: 1.0062x; 1.0024x over previous
; #define GAS __attribute__((address_space(1)))
; template <int DK, int DVS, bool RET> ...
;     ...
;     const int kx = tid % DK, pg = tid / DK;
;     const GAS bf16_t* Qg = (const GAS bf16_t*)Q; const GAS bf16_t* Kg = (const GAS bf16_t*)Kp; const GAS float* LFg = (const GAS float*)LF; const GAS bf16_t* Vg = (const GAS bf16_t*)V;
;     ...
;     GLA_LOAD(0);
.LBB0_52:
	s_bfe_i32 s36, s49, 0x10002
	s_bfe_u32 s63, s49, 0x10002
	s_ashr_i32 s40, s49, 6
	s_cmp_eq_u32 s63, 0
	s_cselect_b64 s[30:31], -1, 0
	s_and_b64 s[42:43], s[30:31], exec
	s_mov_b32 s42, 0x18b69000
	s_cselect_b32 s42, s42, 0x1ad69000
	s_add_u32 s56, s0, s42
	s_addc_u32 s57, s1, 0
	s_lshl_b32 s42, s49, 4
	s_and_b32 s66, s42, 0x380
	s_lshl_b32 s42, s49, 5
	s_and_b32 s42, s42, 0x60
	s_mov_b32 s41, 0
	s_or_b32 s62, s66, s42
	s_mul_hi_i32 s43, s40, 0x1100
	s_mul_i32 s42, s40, 0x1100
	s_and_b32 s40, s36, 0xc0
	s_or_b64 s[44:45], s[40:41], s[42:43]
	s_lshl_b32 s36, s63, 12
	s_add_u32 s36, s3, s36
	v_sub_u32_e32 v28, 63, v79
	s_addc_u32 s40, s48, 0
	s_lshl_b32 s63, s66, 2
	v_cndmask_b32_e64 v28, v28, v79, s[30:31]
	s_add_u32 s64, s36, s63
	v_ashrrev_i32_e32 v29, 31, v28
	s_addc_u32 s65, s40, 0
	s_lshl_b32 s36, s66, 1
	v_lshl_add_u64 v[30:31], s[44:45], 0, v[28:29]
	v_lshl_add_u64 v[24:25], v[12:13], 0, s[36:37]
	v_lshlrev_b64 v[32:33], 13, v[30:31]
	v_lshlrev_b64 v[30:31], 11, v[30:31]
	v_sub_u32_e32 v0, 63, v77
	v_lshl_add_u64 v[34:35], v[24:25], 0, v[30:31]
	v_sub_u32_e32 v30, 63, v80
	v_cndmask_b32_e64 v20, v0, v77, s[30:31]
	v_sub_u32_e32 v4, 63, v78
	v_cndmask_b32_e64 v30, v30, v80, s[30:31]
	v_ashrrev_i32_e32 v21, 31, v20
	v_cndmask_b32_e64 v26, v4, v78, s[30:31]
	v_ashrrev_i32_e32 v31, 31, v30
	v_lshl_add_u64 v[0:1], s[44:45], 0, v[20:21]
	v_ashrrev_i32_e32 v27, 31, v26
	v_lshl_add_u64 v[36:37], s[44:45], 0, v[30:31]
	v_lshl_add_u64 v[22:23], v[10:11], 2, s[64:65]
	v_lshlrev_b64 v[2:3], 13, v[0:1]
	v_lshl_add_u64 v[4:5], s[44:45], 0, v[26:27]
	v_lshlrev_b64 v[38:39], 13, v[36:37]
	v_lshlrev_b64 v[36:37], 11, v[36:37]
	v_readlane_b32 s59, v253, 62
	v_readlane_b32 s51, v254, 0
	v_readlane_b32 s47, v254, 2
	s_mov_b32 s50, s37
	v_readlane_b32 s46, v253, 63
	v_readlane_b32 s61, v254, 1
	v_readlane_b32 s60, v254, 3
	v_lshl_add_u64 v[2:3], v[22:23], 0, v[2:3]
	v_lshlrev_b64 v[0:1], 11, v[0:1]
	v_lshlrev_b64 v[6:7], 13, v[4:5]
	v_lshlrev_b64 v[4:5], 11, v[4:5]
	v_lshl_add_u64 v[36:37], v[24:25], 0, v[36:37]
	v_lshl_add_u64 v[0:1], v[24:25], 0, v[0:1]
	v_lshl_add_u64 v[6:7], v[22:23], 0, v[6:7]
	v_lshl_add_u64 v[4:5], v[24:25], 0, v[4:5]
	v_lshl_add_u64 v[32:33], v[22:23], 0, v[32:33]
	v_lshl_add_u64 v[38:39], v[22:23], 0, v[38:39]
	global_load_dword v132, v[2:3], off
	global_load_ushort v133, v[0:1], off
	global_load_dword v134, v[6:7], off
	global_load_ushort v135, v[4:5], off
	global_load_dword v136, v[32:33], off
	global_load_ushort v137, v[34:35], off
	global_load_dword v138, v[38:39], off
	global_load_ushort v139, v[36:37], off
	v_sub_u32_e32 v36, 63, v83
	v_cndmask_b32_e64 v36, v36, v83, s[30:31]
	v_ashrrev_i32_e32 v37, 31, v36
	v_lshl_add_u64 v[38:39], s[44:45], 0, v[36:37]
	v_lshlrev_b64 v[40:41], 13, v[38:39]
	v_lshlrev_b64 v[38:39], 11, v[38:39]
	v_sub_u32_e32 v0, 63, v81
	v_lshl_add_u64 v[42:43], v[24:25], 0, v[38:39]
	v_sub_u32_e32 v38, 63, v84
	v_cndmask_b32_e64 v32, v0, v81, s[30:31]
	v_sub_u32_e32 v4, 63, v82
	v_cndmask_b32_e64 v38, v38, v84, s[30:31]
	v_ashrrev_i32_e32 v33, 31, v32
	v_cndmask_b32_e64 v34, v4, v82, s[30:31]
	v_ashrrev_i32_e32 v39, 31, v38
	v_lshl_add_u64 v[0:1], s[44:45], 0, v[32:33]
	v_ashrrev_i32_e32 v35, 31, v34
	v_lshl_add_u64 v[44:45], s[44:45], 0, v[38:39]
	v_lshlrev_b64 v[2:3], 13, v[0:1]
	v_lshl_add_u64 v[4:5], s[44:45], 0, v[34:35]
	v_lshlrev_b64 v[46:47], 13, v[44:45]
	v_lshlrev_b64 v[44:45], 11, v[44:45]
	v_lshl_add_u64 v[2:3], v[22:23], 0, v[2:3]
	v_lshlrev_b64 v[0:1], 11, v[0:1]
	v_lshlrev_b64 v[6:7], 13, v[4:5]
	v_lshlrev_b64 v[4:5], 11, v[4:5]
	v_lshl_add_u64 v[44:45], v[24:25], 0, v[44:45]
	v_lshl_add_u64 v[0:1], v[24:25], 0, v[0:1]
	v_lshl_add_u64 v[6:7], v[22:23], 0, v[6:7]
	v_lshl_add_u64 v[4:5], v[24:25], 0, v[4:5]
	v_lshl_add_u64 v[40:41], v[22:23], 0, v[40:41]
	v_lshl_add_u64 v[46:47], v[22:23], 0, v[46:47]
	global_load_dword v140, v[2:3], off
	global_load_ushort v141, v[0:1], off
	global_load_dword v142, v[6:7], off
	global_load_ushort v143, v[4:5], off
	global_load_dword v147, v[40:41], off
	global_load_ushort v150, v[42:43], off
	global_load_dword v151, v[46:47], off
	global_load_ushort v162, v[44:45], off
	v_sub_u32_e32 v44, 63, v87
	v_cndmask_b32_e64 v44, v44, v87, s[30:31]
	v_ashrrev_i32_e32 v45, 31, v44
	v_lshl_add_u64 v[46:47], s[44:45], 0, v[44:45]
	v_lshlrev_b64 v[48:49], 13, v[46:47]
	v_lshlrev_b64 v[46:47], 11, v[46:47]
	v_sub_u32_e32 v0, 63, v85
	v_lshl_add_u64 v[50:51], v[24:25], 0, v[46:47]
	v_sub_u32_e32 v46, 63, v88
	v_cndmask_b32_e64 v40, v0, v85, s[30:31]
	v_sub_u32_e32 v4, 63, v86
	v_cndmask_b32_e64 v46, v46, v88, s[30:31]
	v_ashrrev_i32_e32 v41, 31, v40
	v_cndmask_b32_e64 v42, v4, v86, s[30:31]
	v_ashrrev_i32_e32 v47, 31, v46
	v_lshl_add_u64 v[0:1], s[44:45], 0, v[40:41]
	v_ashrrev_i32_e32 v43, 31, v42
	v_lshl_add_u64 v[52:53], s[44:45], 0, v[46:47]
	v_lshlrev_b64 v[2:3], 13, v[0:1]
	v_lshl_add_u64 v[4:5], s[44:45], 0, v[42:43]
	v_lshlrev_b64 v[54:55], 13, v[52:53]
	v_lshlrev_b64 v[52:53], 11, v[52:53]
	v_lshl_add_u64 v[2:3], v[22:23], 0, v[2:3]
	v_lshlrev_b64 v[0:1], 11, v[0:1]
	v_lshlrev_b64 v[6:7], 13, v[4:5]
	v_lshlrev_b64 v[4:5], 11, v[4:5]
	v_lshl_add_u64 v[52:53], v[24:25], 0, v[52:53]
	v_lshl_add_u64 v[0:1], v[24:25], 0, v[0:1]
	v_lshl_add_u64 v[6:7], v[22:23], 0, v[6:7]
	v_lshl_add_u64 v[4:5], v[24:25], 0, v[4:5]
	v_lshl_add_u64 v[48:49], v[22:23], 0, v[48:49]
	v_lshl_add_u64 v[54:55], v[22:23], 0, v[54:55]
	global_load_dword v210, v[2:3], off
	global_load_ushort v217, v[0:1], off
	global_load_dword v220, v[6:7], off
	global_load_ushort v221, v[4:5], off
	global_load_dword v222, v[48:49], off
	global_load_ushort v223, v[50:51], off
	global_load_dword v224, v[54:55], off
; #define LAS __attribute__((address_space(3)))
; #define GAS __attribute__((address_space(1)))
; template <int DK, int DVS, bool RET> ...
;     ...
;     unsigned aQD = (unsigned)(uintptr_t)(LAS unsigned char*)lds, aKD = aQD + 64 * LK * 2, aSTB = aKD + 64 * LK * 2, aVI = aSTB + DVS * LK * 2,
;              aAT = aVI + 64 * LV * 2, aEL = aAT + 64 * LS * 2, aTOT = aEL + DK * 4;
;     asm volatile("" : "+s"(aQD), "+s"(aVI), "+s"(aAT), "+s"(aEL), "+s"(aTOT), "+s"(aKD), "+s"(aSTB));
;     LAS bf16_t* QD = (LAS bf16_t*)(uintptr_t)aQD; LAS bf16_t* VI = (LAS bf16_t*)(uintptr_t)aVI; LAS bf16_t* AT = (LAS bf16_t*)(uintptr_t)aAT;
;     LAS float* EL = (LAS float*)(uintptr_t)aEL; LAS float* TOT = (LAS float*)(uintptr_t)aTOT;
;     LAS bf16_t* KD = (LAS bf16_t*)(uintptr_t)aKD; LAS bf16_t* STB = (LAS bf16_t*)(uintptr_t)aSTB;
;     static_assert(2 * 64 * LK * 2 + DVS * LK * 2 + 64 * LV * 2 + 64 * LS * 2 + DK * 4 + 2048 <= 159744, "GLA LDS map");
;     const int wid = tid >> 6, lane = tid & 63, l16 = lane & 15, quad = lane >> 4;
;     const int tr = wid >> 1, tv = wid / WPV, kt0 = (wid % WPV) * TPW;
;     const int vtr = (int)aVI + (8 * quad + (l16 >> 2)) * (LV * 2) + 8 * (lane & 3);
;     const int ktr = (int)aKD + (8 * quad + (l16 >> 2)) * (LK * 2) + 8 * (lane & 3);
;     ...
;     f32x4 st[TPW];
; #pragma unroll
;     for (int t = 0; t < TPW; ++t) st[t] = (f32x4){0.f, 0.f, 0.f, 0.f};
;     ...
;     typedef short vvec_t __attribute__((ext_vector_type(VPT)));
;     constexpr int NQV = RET ? 4 : 1, NLC = RET ? 1 : PPT;
;     bf16x8 qv[NQV], kv[NQV]; float lc[NLC]; bf16_t qr[NLC]; vvec_t vraw;
;     const int kx = tid % DK, pg = tid / DK;
;     const GAS bf16_t* Qg = (const GAS bf16_t*)Q; const GAS bf16_t* Kg = (const GAS bf16_t*)Kp; const GAS float* LFg = (const GAS float*)LF; const GAS bf16_t* Vg = (const GAS bf16_t*)V;
;     ...
;     GLA_LOAD(0);
	global_load_ushort v225, v[52:53], off
	v_sub_u32_e32 v52, 63, v91
	v_cndmask_b32_e64 v52, v52, v91, s[30:31]
	v_ashrrev_i32_e32 v53, 31, v52
	v_lshl_add_u64 v[54:55], s[44:45], 0, v[52:53]
	v_sub_u32_e32 v0, 63, v89
	v_lshlrev_b64 v[56:57], 13, v[54:55]
	v_lshlrev_b64 v[54:55], 11, v[54:55]
	v_cndmask_b32_e64 v48, v0, v89, s[30:31]
	v_sub_u32_e32 v4, 63, v90
	v_lshl_add_u64 v[58:59], v[24:25], 0, v[54:55]
	v_sub_u32_e32 v54, 63, v92
	v_ashrrev_i32_e32 v49, 31, v48
	v_cndmask_b32_e64 v50, v4, v90, s[30:31]
	v_cndmask_b32_e64 v54, v54, v92, s[30:31]
	v_lshl_add_u64 v[0:1], s[44:45], 0, v[48:49]
	v_ashrrev_i32_e32 v51, 31, v50
	v_ashrrev_i32_e32 v55, 31, v54
	v_lshlrev_b64 v[2:3], 13, v[0:1]
	v_lshl_add_u64 v[4:5], s[44:45], 0, v[50:51]
	v_lshl_add_u64 v[60:61], s[44:45], 0, v[54:55]
	v_lshl_add_u64 v[2:3], v[22:23], 0, v[2:3]
	v_lshlrev_b64 v[0:1], 11, v[0:1]
	v_lshlrev_b64 v[6:7], 13, v[4:5]
	v_lshlrev_b64 v[4:5], 11, v[4:5]
	v_lshlrev_b64 v[62:63], 13, v[60:61]
	v_lshlrev_b64 v[60:61], 11, v[60:61]
	v_lshl_add_u64 v[0:1], v[24:25], 0, v[0:1]
	v_lshl_add_u64 v[6:7], v[22:23], 0, v[6:7]
	v_lshl_add_u64 v[4:5], v[24:25], 0, v[4:5]
	v_lshl_add_u64 v[56:57], v[22:23], 0, v[56:57]
	v_lshl_add_u64 v[62:63], v[22:23], 0, v[62:63]
	v_lshl_add_u64 v[60:61], v[24:25], 0, v[60:61]
	global_load_dword v226, v[2:3], off
	global_load_ushort v227, v[0:1], off
	global_load_dword v228, v[6:7], off
	global_load_ushort v229, v[4:5], off
	global_load_dword v230, v[56:57], off
	global_load_ushort v231, v[58:59], off
	global_load_dword v232, v[62:63], off
	global_load_ushort v233, v[60:61], off
	v_sub_u32_e32 v2, 63, v93
	s_lshl_b32 s36, s62, 1
	v_cndmask_b32_e64 v56, v2, v93, s[30:31]
	v_lshlrev_b32_e32 v2, 2, v10
	s_movk_i32 s40, 0x50
	s_add_u32 s44, s56, s36
	v_lshlrev_b32_e32 v1, 1, v9
	v_lshlrev_b32_e32 v0, 1, v8
	v_add_u32_e32 v153, s61, v2
	v_add_u32_e32 v154, s51, v2
	v_mul_lo_u32 v2, v93, s40
	s_addc_u32 s45, s57, 0
	v_add_u32_e32 v4, s50, v1
	v_add_u32_e32 v5, s60, v0
	v_add3_u32 v155, s59, v2, v14
	v_add3_u32 v156, s47, v96, v1
	v_add_u32_e32 v6, s60, v1
	v_add3_u32 v158, s46, v99, v1
	v_lshl_add_u64 v[2:3], s[44:45], 0, v[144:145]
	v_mov_b32_e32 v1, v145
	v_add_u32_e32 v64, s59, v76
	v_lshl_add_u64 v[60:61], v[2:3], 0, v[0:1]
	v_add_u32_e32 v0, s47, v101
	v_add_u32_e32 v2, v5, v102
	v_add_u32_e32 v3, v5, v104
	v_lshlrev_b32_e32 v5, 1, v18
	v_add_u32_e32 v157, v64, v15
	v_add_u32_e32 v159, v64, v100
	v_lshl_add_u32 v1, v8, 2, s51
	v_add_u32_e32 v163, s50, v5
	v_add_u32_e32 v164, s47, v5
	v_lshlrev_b32_e32 v5, 1, v95
	v_cndmask_b32_e64 v62, v251, v97, s[30:31]
	v_cndmask_b32_e64 v64, v252, v105, s[30:31]
	v_cndmask_b32_e64 v66, v198, v107, s[30:31]
	v_cndmask_b32_e64 v68, v114, v109, s[30:31]
	v_add_u32_e32 v211, v0, v102
	v_add_u32_e32 v212, v0, v104
	v_mov_b32_e32 v0, 0
	v_ashrrev_i32_e32 v57, 31, v56
	v_lshl_add_u64 v[58:59], v[16:17], 0, s[36:37]
	v_lshl_add_u32 v152, v146, 2, s61
	v_add_u32_e32 v160, s50, v117
	v_add_u32_e32 v161, s47, v117
	v_add_u32_e32 v165, s50, v118
	v_add_u32_e32 v166, s47, v118
	v_add_u32_e32 v167, s50, v119
	v_add_u32_e32 v168, s47, v119
	v_add_u32_e32 v169, s50, v120
	v_add_u32_e32 v170, s47, v120
	v_add_u32_e32 v171, s50, v121
	v_add_u32_e32 v172, s47, v121
	v_add_u32_e32 v173, s50, v122
	v_add_u32_e32 v174, s47, v122
	v_add_u32_e32 v175, s50, v123
	v_add_u32_e32 v176, s47, v123
	v_add_u32_e32 v177, s50, v124
	v_add_u32_e32 v178, s47, v124
	v_add_u32_e32 v179, s50, v125
	v_add_u32_e32 v180, s47, v125
	v_add_u32_e32 v181, s50, v126
	v_add_u32_e32 v182, s47, v126
	v_add_u32_e32 v183, s50, v127
	v_add_u32_e32 v184, s47, v127
	v_add_u32_e32 v185, s50, v128
	v_add_u32_e32 v199, s47, v128
	v_add_u32_e32 v200, s50, v129
	v_add_u32_e32 v201, s47, v129
	v_add_u32_e32 v202, s50, v130
	v_add_u32_e32 v203, s47, v130
	v_add_u32_e32 v204, s50, v131
	v_add_u32_e32 v205, s47, v131
	v_add3_u32 v206, s46, v19, v5
	v_add3_u32 v207, s46, v106, v5
	v_add3_u32 v208, s46, v108, v5
	v_add3_u32 v209, s46, v250, v5
	v_ashrrev_i32_e32 v63, 31, v62
	v_ashrrev_i32_e32 v65, 31, v64
	v_ashrrev_i32_e32 v67, 31, v66
	v_ashrrev_i32_e32 v69, 31, v68
	v_add_u32_e32 v213, v2, v103
	v_add_u32_e32 v214, v3, v103
	v_add_u32_e32 v215, v4, v94
	v_add_u32_e32 v216, v6, v98
	v_add_u32_e32 v218, v1, v115
	v_add_u32_e32 v219, v1, v116
	s_mov_b32 s36, s41
	v_mov_b32_e32 v1, v0
	v_mov_b32_e32 v2, v0
	v_mov_b32_e32 v3, v0
	v_mov_b32_e32 v4, v0
	v_mov_b32_e32 v5, v0
	v_mov_b32_e32 v6, v0
	v_mov_b32_e32 v7, v0
	v_mov_b32_e32 v71, v0
	v_mov_b32_e32 v72, v0
	v_mov_b32_e32 v73, v0
	v_mov_b32_e32 v74, v0
	v_mov_b32_e32 v75, v0
	v_mov_b32_e32 v234, v0
	v_mov_b32_e32 v70, v0
	v_lshlrev_b32_e32 v22, 2, v10
	v_add_lshl_u32 v23, s66, v10, 1
	v_lshl_add_u32 v21, v20, 11, v23
	v_lshl_add_u32 v20, v20, 13, v22
	v_lshl_add_u32 v27, v26, 11, v23
	v_lshl_add_u32 v26, v26, 13, v22
	v_lshl_add_u32 v29, v28, 11, v23
	v_lshl_add_u32 v28, v28, 13, v22
	v_lshl_add_u32 v31, v30, 11, v23
	v_lshl_add_u32 v30, v30, 13, v22
	v_lshl_add_u32 v33, v32, 11, v23
	v_lshl_add_u32 v32, v32, 13, v22
	v_lshl_add_u32 v35, v34, 11, v23
	v_lshl_add_u32 v34, v34, 13, v22
	v_lshl_add_u32 v37, v36, 11, v23
	v_lshl_add_u32 v36, v36, 13, v22
	v_lshl_add_u32 v39, v38, 11, v23
	v_lshl_add_u32 v38, v38, 13, v22
	v_lshl_add_u32 v41, v40, 11, v23
	v_lshl_add_u32 v40, v40, 13, v22
	v_lshl_add_u32 v43, v42, 11, v23
	v_lshl_add_u32 v42, v42, 13, v22
	v_lshl_add_u32 v45, v44, 11, v23
	v_lshl_add_u32 v44, v44, 13, v22
	v_lshl_add_u32 v47, v46, 11, v23
	v_lshl_add_u32 v46, v46, 13, v22
	v_lshl_add_u32 v49, v48, 11, v23
	v_lshl_add_u32 v48, v48, 13, v22
	v_lshl_add_u32 v51, v50, 11, v23
	v_lshl_add_u32 v50, v50, 13, v22
	v_lshl_add_u32 v53, v52, 11, v23
	v_lshl_add_u32 v52, v52, 13, v22
	v_lshl_add_u32 v55, v54, 11, v23
	v_lshl_add_u32 v54, v54, 13, v22
	v_and_b32_e32 v110, 15, v148
	v_bfe_u32 v111, v148, 4, 2
	v_lshlrev_b32_e32 v111, 2, v111
	v_sub_u32_e32 v110, v110, v111
	v_mul_i32_i24_e32 v111, 0x10e, v110
	v_add_u32_e32 v213, v213, v111
	v_add_u32_e32 v214, v214, v111
	v_lshlrev_b32_e32 v110, 2, v110
	v_sub_u32_e32 v218, v218, v110
	v_sub_u32_e32 v219, v219, v110
	s_branch .LBB0_54
; #define LAS __attribute__((address_space(3)))
; template <int DK, int DVS, bool RET> ...
;     ...
;         {
;             const int tcs = (wid & 1) * 2;
;             f32x4 a0 = {0.f, 0.f, 0.f, 0.f}, a1 = {0.f, 0.f, 0.f, 0.f};
; #pragma unroll
;             for (int kk = 0; kk < DK / 32; ++kk) {
;                 const bf16x8 af = *(const LAS bf16x8*)(QD + (tr * 16 + l16) * LK + kk * 32 + quad * 8);
;                 const bf16x8 b0 = *(const LAS bf16x8*)(KD + (tcs * 16 + l16) * LK + kk * 32 + quad * 8);
;                 const bf16x8 b1 = *(const LAS bf16x8*)(KD + ((tcs + 1) * 16 + l16) * LK + kk * 32 + quad * 8);
;                 a0 = __builtin_amdgcn_mfma_f32_16x16x32_bf16(af, b0, a0, 0, 0, 0);
;                 a1 = __builtin_amdgcn_mfma_f32_16x16x32_bf16(af, b1, a1, 0, 0, 0);
;                 asm volatile("" ::: "memory");
;             }
; #pragma unroll
;             for (int j = 0; j < 4; ++j) { const int p = tr * 16 + quad * 4 + j, s0 = tcs * 16 + l16, s1 = s0 + 16;
;                 AT[p * LS + s0] = f2bf((s0 <= p) ? a0[j] : 0.f); AT[p * LS + s1] = f2bf((s1 <= p) ? a1[j] : 0.f); }
;         }
;         GLA_BAR();
; #pragma unroll
;         for (int t = 0; t < NOT; ++t) { const int tc = (wid & 1) * NOT + t; f32x4 acc = {0.f, 0.f, 0.f, 0.f};
; #pragma unroll
;             for (int kk = 0; kk < DK / 32; ++kk) {
;                 const bf16x8 af = *(const LAS bf16x8*)(QD + (tr * 16 + l16) * LK + kk * 32 + quad * 8);
;                 const bf16x8 bf = *(const LAS bf16x8*)(STB + (tc * 16 + l16) * LK + kk * 32 + quad * 8);
;                 acc = __builtin_amdgcn_mfma_f32_16x16x32_bf16(af, bf, acc, 0, 0, 0);
;                 if ((kk & 3) == 3) asm volatile("" ::: "memory"); }
;             { s16x4 v00, v01, v10, v11; const int vb = vtr + tc * 32;
;                 TRR(v00, vb, 0); TRR(v01, vb, 4 * LV * 2); TRR(v10, vb, 32 * LV * 2); TRR(v11, vb, 36 * LV * 2);
;                 const bf16x8 a0 = *(const LAS bf16x8*)(AT + (tr * 16 + l16) * LS + quad * 8), a1 = *(const LAS bf16x8*)(AT + (tr * 16 + l16) * LS + 32 + quad * 8);
;                 asm volatile("s_waitcnt lgkmcnt(0)" ::: "memory"); __builtin_amdgcn_sched_barrier(0);
;                 acc = __builtin_amdgcn_mfma_f32_16x16x32_bf16(a0, TRFRAG(v00, v01), acc, 0, 0, 0);
;                 acc = __builtin_amdgcn_mfma_f32_16x16x32_bf16(a1, TRFRAG(v10, v11), acc, 0, 0, 0); }
; #pragma unroll
.LBB0_53:
	s_waitcnt lgkmcnt(0)
	s_barrier
	ds_read_b128 v[70:73], v215
	ds_read_b128 v[234:237], v156
	ds_read_b128 v[238:241], v156 offset:4352
	ds_read_b128 v[242:245], v215 offset:64
	s_waitcnt lgkmcnt(2)
	v_mfma_f32_16x16x32_bf16 v[234:237], v[70:73], v[234:237], 0
	s_waitcnt lgkmcnt(1)
	v_mfma_f32_16x16x32_bf16 v[70:73], v[70:73], v[238:241], 0
	ds_read_b128 v[238:241], v156 offset:64
	ds_read_b128 v[246:249], v156 offset:4416
	s_waitcnt lgkmcnt(1)
	v_mfma_f32_16x16x32_bf16 v[234:237], v[242:245], v[238:241], v[234:237]
	ds_read_b128 v[238:241], v215 offset:128
	s_waitcnt lgkmcnt(1)
	v_mfma_f32_16x16x32_bf16 v[70:73], v[242:245], v[246:249], v[70:73]
	ds_read_b128 v[242:245], v156 offset:128
	ds_read_b128 v[246:249], v156 offset:4480
	s_waitcnt lgkmcnt(1)
	v_mfma_f32_16x16x32_bf16 v[234:237], v[238:241], v[242:245], v[234:237]
	ds_read_b128 v[242:245], v215 offset:192
	s_waitcnt lgkmcnt(1)
	v_mfma_f32_16x16x32_bf16 v[70:73], v[238:241], v[246:249], v[70:73]
	ds_read_b128 v[238:241], v156 offset:192
	ds_read_b128 v[246:249], v156 offset:4544
	s_waitcnt lgkmcnt(0)
	v_mfma_f32_16x16x32_bf16 v[70:73], v[242:245], v[246:249], v[70:73]
	v_mfma_f32_16x16x32_bf16 v[234:237], v[242:245], v[238:241], v[234:237]
	s_nop 6
	v_cvt_pk_bf16_f32 v70, v70, s0
	v_cndmask_b32_e64 v70, v70, 0, s[16:17]
	ds_write_b16 v206, v70 offset:32
	v_cvt_pk_bf16_f32 v70, v235, s0
	v_cndmask_b32_e64 v70, v70, 0, s[18:19]
	ds_write_b16 v207, v70
	v_cvt_pk_bf16_f32 v70, v71, s0
	v_cndmask_b32_e64 v70, v70, 0, s[20:21]
	ds_write_b16 v207, v70 offset:32
	v_cvt_pk_bf16_f32 v70, v236, s0
	v_cndmask_b32_e64 v70, v70, 0, s[22:23]
	ds_write_b16 v208, v70
	v_cvt_pk_bf16_f32 v70, v72, s0
	v_cndmask_b32_e64 v70, v70, 0, s[24:25]
	ds_write_b16 v208, v70 offset:32
	v_cvt_pk_bf16_f32 v70, v237, s0
	v_cndmask_b32_e64 v70, v70, 0, s[26:27]
	v_cvt_pk_bf16_f32 v74, v234, s0
	ds_write_b16 v209, v70
	v_cvt_pk_bf16_f32 v70, v73, s0
	v_cndmask_b32_e64 v74, v74, 0, s[14:15]
	v_cndmask_b32_e64 v70, v70, 0, s[28:29]
	ds_write_b16 v206, v74
	ds_write_b16 v209, v70 offset:32
	s_waitcnt lgkmcnt(0)
	s_barrier
	ds_read_b128 v[70:73], v215
	ds_read_b128 v[234:237], v215 offset:64
	ds_read_b128 v[238:241], v216
	ds_read_b128 v[242:245], v216 offset:64
	s_waitcnt lgkmcnt(1)
	v_mfma_f32_16x16x32_bf16 v[70:73], v[70:73], v[238:241], 0
	ds_read_b128 v[238:241], v215 offset:128
	s_waitcnt lgkmcnt(1)
	v_mfma_f32_16x16x32_bf16 v[70:73], v[234:237], v[242:245], v[70:73]
	ds_read_b128 v[234:237], v215 offset:192
	ds_read_b128 v[242:245], v216 offset:128
	ds_read_b128 v[246:249], v216 offset:192
	s_waitcnt lgkmcnt(1)
	v_mfma_f32_16x16x32_bf16 v[70:73], v[238:241], v[242:245], v[70:73]
	s_waitcnt lgkmcnt(0)
	v_mfma_f32_16x16x32_bf16 v[70:73], v[234:237], v[246:249], v[70:73]
	ds_read_b64_tr_b16 v[234:235], v157 offset:0
	ds_read_b64_tr_b16 v[236:237], v157 offset:0x140
	ds_read_b64_tr_b16 v[238:239], v157 offset:0xa00
	ds_read_b64_tr_b16 v[240:241], v157 offset:0xb40
	ds_read_b128 v[242:245], v158
	ds_read_b128 v[246:249], v158 offset:64
	s_waitcnt lgkmcnt(0)
	s_waitcnt lgkmcnt(1)
	v_mfma_f32_16x16x32_bf16 v[70:73], v[242:245], v[234:237], v[70:73]
	v_lshl_add_u64 v[74:75], s[44:45], 0, v[62:63]
	v_lshlrev_b64 v[74:75], 11, v[74:75]
	v_lshl_add_u64 v[74:75], v[60:61], 0, v[74:75]
	s_waitcnt lgkmcnt(0)
	v_mfma_f32_16x16x32_bf16 v[70:73], v[246:249], v[238:241], v[70:73]
	s_nop 7
	v_cvt_pk_bf16_f32 v70, v70, s0
	global_store_short v[74:75], v70, off
	v_lshl_add_u64 v[74:75], s[44:45], 0, v[64:65]
	v_cvt_pk_bf16_f32 v110, v71, s0
	v_lshlrev_b64 v[70:71], 11, v[74:75]
	v_lshl_add_u64 v[70:71], v[60:61], 0, v[70:71]
	global_store_short v[70:71], v110, off
	v_lshl_add_u64 v[70:71], s[44:45], 0, v[66:67]
	v_lshlrev_b64 v[70:71], 11, v[70:71]
	v_cvt_pk_bf16_f32 v72, v72, s0
	v_lshl_add_u64 v[70:71], v[60:61], 0, v[70:71]
	global_store_short v[70:71], v72, off
	v_lshl_add_u64 v[70:71], s[44:45], 0, v[68:69]
	v_lshlrev_b64 v[70:71], 11, v[70:71]
	v_cvt_pk_bf16_f32 v72, v73, s0
	v_lshl_add_u64 v[70:71], v[60:61], 0, v[70:71]
	global_store_short v[70:71], v72, off
	ds_read_b64_tr_b16 v[70:71], v159 offset:0
	ds_read_b64_tr_b16 v[72:73], v159 offset:0x140
	ds_read_b64_tr_b16 v[234:235], v159 offset:0xa00
	ds_read_b64_tr_b16 v[236:237], v159 offset:0xb40
	ds_read_b64_tr_b16 v[238:239], v211 offset:0
	ds_read_b64_tr_b16 v[240:241], v211 offset:0x440
	ds_read_b64_tr_b16 v[242:243], v211 offset:0x2200
	ds_read_b64_tr_b16 v[244:245], v211 offset:0x2640
	ds_read_b64_tr_b16 v[246:247], v212 offset:0
	ds_read_b64_tr_b16 v[248:249], v212 offset:0x440
	ds_read_b64_tr_b16 v[110:111], v212 offset:0x2200
	ds_read_b64_tr_b16 v[112:113], v212 offset:0x2640
	s_waitcnt lgkmcnt(0)
	s_nop 0
	v_mfma_f32_16x16x32_bf16 v[0:3], v[238:241], v[70:73], v[0:3]
	ds_read_b128 v[238:241], v218
	s_add_i32 s41, s41, -1
	v_mfma_f32_16x16x32_bf16 v[4:7], v[246:249], v[70:73], v[4:7]
	ds_read_b128 v[246:249], v219
	s_mov_b32 s36, s40
	v_mfma_f32_16x16x32_bf16 v[0:3], v[242:245], v[234:237], v[0:3]
	v_mfma_f32_16x16x32_bf16 v[4:7], v[110:113], v[234:237], v[4:7]
	s_waitcnt lgkmcnt(1)
	s_nop 5
	v_pk_mul_f32 v[0:1], v[0:1], v[238:239]
	v_pk_mul_f32 v[2:3], v[2:3], v[240:241]
	s_waitcnt lgkmcnt(0)
	v_pk_mul_f32 v[4:5], v[4:5], v[246:247]
	v_pk_mul_f32 v[6:7], v[6:7], v[248:249]
	s_cmpk_lg_i32 s41, 0xffbc
	s_cbranch_scc0 .LBB0_51
; #define LAS __attribute__((address_space(3)))
; #define GAS __attribute__((address_space(1)))
; __device__ __forceinline__ bf16_t f2bf(float x) { return (bf16_t)(cvt_pk_bf16(x, x) & 0xffffu); }
; __device__ __forceinline__ float bf2f(bf16_t v) { return __uint_as_float((unsigned)v << 16); }
; template <int DK, int DVS, bool RET> ...
;     ...
;         GLA_BAR();
;         {
; #pragma unroll
;             for (int t = 0; t < TPW; ++t)
; #pragma unroll
;                 for (int j = 0; j < 4; ++j) STB[(tv * 16 + quad * 4 + j) * LK + (kt0 + t) * 16 + l16] = f2bf(st[t][j]);
;             { const int p = tid >> 3, vg = tid & 7; const long row = R0 + (dir ? 63 - p : p); vraw = *(const GAS vvec_t*)(Vg + row * ldv + vcol0 + vg * VPT); }
;             float bl;
;             if constexpr (RET) {
;                 static_assert(!RET || DK == 256, "retention prep: 64 x 256 = 2048 eight-wide items, four per thread");
;                 bl = 64.f * lg;
; #pragma unroll
;                 for (int j = 0; j < 4; ++j) { const int it = tid + 512 * j, p = it & 63, k0 = (it >> 6) * 8; const float bb = (float)(p + 1) * lg;
;                     const float eq = __expf(bb), ek = __expf(-bb); float a[8], c[8];
; #pragma unroll
;                     for (int e = 0; e < 8; ++e) { a[e] = bf2f((bf16_t)qv[j][e]) * eq; c[e] = bf2f((bf16_t)kv[j][e]) * ek; }
;                     *(LAS u32x4*)(QD + p * LK + k0) = pack8(a); *(LAS u32x4*)(KD + p * LK + k0) = pack8(c); }
;             } else {
;                 float c = 0.f;
; #pragma unroll
;                 for (int i = 0; i < PPT; ++i) c += lc[i];
;                 TOT[pg * 128 + kx] = c;
;                 GLA_BAR();
;                 float off = 0.f; bl = 0.f;
; #pragma unroll
;                 for (int g = 0; g < NPG; ++g) { const float t = TOT[g * 128 + kx]; if (g < pg) off += t; bl += t; }
;                 float bb = off;
; #pragma unroll
;                 for (int i = 0; i < PPT; ++i) { const int p = pg * PPT + i;
;                     const float qf = bf2f(qr[i]), kf = 1.f - __expf(lc[i]); bb += lc[i];
;                     QD[p * LK + kx] = f2bf(qf * __expf(bb)); KD[p * LK + kx] = f2bf(kf * __expf(-bb)); }
;             }
;             if (pg == 0) EL[kx] = __expf(bl);
;             { const int p = tid >> 3, vg = tid & 7; *(LAS vvec_t*)(VI + p * LV + vg * VPT) = vraw; }
;         }
;         if (step + 1 < 68) GLA_LOAD(step + 1);
.LBB0_54:
	v_cvt_pk_bf16_f32 v74, v0, v1
	v_cvt_pk_bf16_f32 v75, v2, v3
	v_cvt_pk_bf16_f32 v110, v4, v5
	v_cvt_pk_bf16_f32 v111, v6, v7
	s_waitcnt lgkmcnt(0)
	s_barrier
	ds_write_b64 v213, v[74:75]
	ds_write_b64 v214, v[110:111]
	s_waitcnt vmcnt(0)
	v_add_f32_e32 v72, 0, v132
	v_add_f32_e32 v72, v134, v72
	v_add_f32_e32 v72, v136, v72
	v_add_f32_e32 v72, v138, v72
	v_add_f32_e32 v72, v140, v72
	s_cmp_gt_u32 s36, 3
	v_add_f32_e32 v72, v142, v72
	s_cselect_b32 s40, 0x47, 3
	v_add_f32_e32 v72, v147, v72
	s_add_i32 s40, s40, s41
	v_add_f32_e32 v72, v151, v72
	s_and_b64 s[44:45], s[30:31], exec
	v_add_f32_e32 v72, v210, v72
	s_cselect_b32 s40, s36, s40
	v_add_f32_e32 v72, v220, v72
	s_lshl_b32 s40, s40, 6
	v_add_f32_e32 v72, v222, v72
	s_ashr_i32 s45, s40, 31
	v_add_f32_e32 v72, v224, v72
	s_add_u32 s44, s42, s40
	v_add_f32_e32 v72, v226, v72
	s_addc_u32 s45, s43, s45
	v_add_f32_e32 v72, v228, v72
	v_lshl_add_u64 v[70:71], s[44:45], 0, v[56:57]
	v_add_f32_e32 v72, v230, v72
	v_lshlrev_b64 v[70:71], 11, v[70:71]
	v_add_f32_e32 v72, v232, v72
	v_lshl_add_u64 v[70:71], v[58:59], 0, v[70:71]
	ds_write_b32 v152, v72
	global_load_dwordx2 v[70:71], v[70:71], off
	s_waitcnt lgkmcnt(0)
	s_barrier
	s_add_i32 s39, s36, 1
	s_min_i32 s39, s39, 0x43
	s_cmp_gt_u32 s39, 3
	s_cselect_b32 s38, 0x47, 3
	s_sub_i32 s38, s38, s39
	s_and_b64 s[54:55], s[30:31], exec
	s_cselect_b32 s38, s39, s38
	s_lshl_b32 s38, s38, 6
	s_ashr_i32 s39, s38, 31
	s_add_u32 s54, s42, s38
	s_addc_u32 s55, s43, s39
	s_lshl_b64 s[38:39], s[54:55], 11
	s_add_u32 s38, s38, s90
	s_addc_u32 s39, s39, s91
	s_lshl_b64 s[54:55], s[54:55], 13
	s_add_u32 s54, s54, s64
	s_addc_u32 s55, s55, s65
	ds_read2st64_b32 v[72:73], v153 offset1:2
	s_waitcnt lgkmcnt(0)
	v_add_f32_e32 v72, 0, v72
	v_cndmask_b32_e64 v74, 0, v72, s[6:7]
	v_add_f32_e32 v75, v73, v74
	v_cndmask_b32_e64 v110, v74, v75, s[8:9]
	ds_read2st64_b32 v[74:75], v153 offset0:4 offset1:6
	v_mul_f32_e32 v111, 0x3fb8aa3b, v132
	v_mul_f32_e32 v112, 0xbfb8aa3b, v132
	s_waitcnt lgkmcnt(0)
	v_add_f32_e32 v113, v74, v110
	v_cndmask_b32_e64 v110, v110, v113, s[10:11]
	v_add_f32_e32 v113, v75, v110
	v_cndmask_b32_e64 v110, v110, v113, s[12:13]
	v_mul_f32_e32 v113, 0xbfb8aa3b, v110
	v_mul_f32_e32 v110, 0x3fb8aa3b, v110
	v_exp_f32_e32 v113, v113
	v_exp_f32_e32 v110, v110
	global_load_dword v132, v20, s[54:55]
	v_exp_f32_e32 v111, v111
	v_exp_f32_e32 v112, v112
	v_mul_f32_e32 v110, v110, v111
	v_mul_f32_e32 v113, v113, v112
	v_sub_f32_e32 v111, 1.0, v111
	v_lshlrev_b32_e32 v112, 16, v133
	global_load_ushort v133, v21, s[38:39]
	v_mul_f32_e32 v111, v111, v113
	v_mul_f32_e32 v112, v110, v112
	v_cvt_pk_bf16_f32 v111, v111, s0
	v_cvt_pk_bf16_f32 v112, v112, s0
	ds_write_b16 v160, v112
	ds_write_b16 v161, v111
	v_mul_f32_e32 v111, 0x3fb8aa3b, v134
	v_mul_f32_e32 v112, 0xbfb8aa3b, v134
	global_load_dword v134, v26, s[54:55]
	v_exp_f32_e32 v111, v111
	v_exp_f32_e32 v112, v112
	v_mul_f32_e32 v110, v110, v111
	v_mul_f32_e32 v113, v113, v112
	v_sub_f32_e32 v111, 1.0, v111
	v_lshlrev_b32_e32 v112, 16, v135
	global_load_ushort v135, v27, s[38:39]
	v_mul_f32_e32 v111, v111, v113
	v_mul_f32_e32 v112, v110, v112
	v_cvt_pk_bf16_f32 v111, v111, s0
	v_cvt_pk_bf16_f32 v112, v112, s0
	ds_write_b16 v163, v112
	ds_write_b16 v164, v111
	v_mul_f32_e32 v111, 0x3fb8aa3b, v136
	v_mul_f32_e32 v112, 0xbfb8aa3b, v136
	global_load_dword v136, v28, s[54:55]
	v_exp_f32_e32 v111, v111
	v_exp_f32_e32 v112, v112
	v_mul_f32_e32 v110, v110, v111
	v_mul_f32_e32 v113, v113, v112
	v_sub_f32_e32 v111, 1.0, v111
	v_lshlrev_b32_e32 v112, 16, v137
	global_load_ushort v137, v29, s[38:39]
	v_mul_f32_e32 v111, v111, v113
	v_mul_f32_e32 v112, v110, v112
	v_cvt_pk_bf16_f32 v111, v111, s0
	v_cvt_pk_bf16_f32 v112, v112, s0
	ds_write_b16 v165, v112
	ds_write_b16 v166, v111
	v_mul_f32_e32 v111, 0x3fb8aa3b, v138
	v_mul_f32_e32 v112, 0xbfb8aa3b, v138
	global_load_dword v138, v30, s[54:55]
	v_exp_f32_e32 v111, v111
	v_exp_f32_e32 v112, v112
	v_mul_f32_e32 v110, v110, v111
	v_mul_f32_e32 v113, v113, v112
	v_sub_f32_e32 v111, 1.0, v111
	v_lshlrev_b32_e32 v112, 16, v139
	global_load_ushort v139, v31, s[38:39]
	v_mul_f32_e32 v111, v111, v113
	v_mul_f32_e32 v112, v110, v112
	v_cvt_pk_bf16_f32 v111, v111, s0
	v_cvt_pk_bf16_f32 v112, v112, s0
	ds_write_b16 v167, v112
	ds_write_b16 v168, v111
	v_mul_f32_e32 v111, 0x3fb8aa3b, v140
	v_mul_f32_e32 v112, 0xbfb8aa3b, v140
	global_load_dword v140, v32, s[54:55]
	v_exp_f32_e32 v111, v111
	v_exp_f32_e32 v112, v112
	v_mul_f32_e32 v110, v110, v111
	v_mul_f32_e32 v113, v113, v112
	v_sub_f32_e32 v111, 1.0, v111
	v_lshlrev_b32_e32 v112, 16, v141
	global_load_ushort v141, v33, s[38:39]
	v_mul_f32_e32 v111, v111, v113
	v_mul_f32_e32 v112, v110, v112
	v_cvt_pk_bf16_f32 v111, v111, s0
	v_cvt_pk_bf16_f32 v112, v112, s0
	ds_write_b16 v169, v112
	ds_write_b16 v170, v111
	v_mul_f32_e32 v111, 0x3fb8aa3b, v142
	v_mul_f32_e32 v112, 0xbfb8aa3b, v142
	global_load_dword v142, v34, s[54:55]
	v_exp_f32_e32 v111, v111
	v_exp_f32_e32 v112, v112
	v_mul_f32_e32 v110, v110, v111
	v_mul_f32_e32 v113, v113, v112
	v_sub_f32_e32 v111, 1.0, v111
	v_lshlrev_b32_e32 v112, 16, v143
	global_load_ushort v143, v35, s[38:39]
	v_mul_f32_e32 v111, v111, v113
	v_mul_f32_e32 v112, v110, v112
	v_cvt_pk_bf16_f32 v111, v111, s0
	v_cvt_pk_bf16_f32 v112, v112, s0
	ds_write_b16 v171, v112
	ds_write_b16 v172, v111
	v_mul_f32_e32 v111, 0x3fb8aa3b, v147
; __device__ __forceinline__ bf16_t f2bf(float x) { return (bf16_t)(cvt_pk_bf16(x, x) & 0xffffu); }
; __device__ __forceinline__ float bf2f(bf16_t v) { return __uint_as_float((unsigned)v << 16); }
; template <int DK, int DVS, bool RET> ...
;     ...
;                 float bb = off;
; #pragma unroll
;                 for (int i = 0; i < PPT; ++i) { const int p = pg * PPT + i;
;                     const float qf = bf2f(qr[i]), kf = 1.f - __expf(lc[i]); bb += lc[i];
;                     QD[p * LK + kx] = f2bf(qf * __expf(bb)); KD[p * LK + kx] = f2bf(kf * __expf(-bb)); }
;             }
;             if (pg == 0) EL[kx] = __expf(bl);
	v_mul_f32_e32 v112, 0xbfb8aa3b, v147
	global_load_dword v147, v36, s[54:55]
	v_exp_f32_e32 v111, v111
	v_exp_f32_e32 v112, v112
	v_mul_f32_e32 v110, v110, v111
	v_mul_f32_e32 v113, v113, v112
	v_sub_f32_e32 v111, 1.0, v111
	v_lshlrev_b32_e32 v112, 16, v150
	global_load_ushort v150, v37, s[38:39]
	v_mul_f32_e32 v111, v111, v113
	v_mul_f32_e32 v112, v110, v112
	v_cvt_pk_bf16_f32 v111, v111, s0
	v_cvt_pk_bf16_f32 v112, v112, s0
	ds_write_b16 v173, v112
	ds_write_b16 v174, v111
	v_mul_f32_e32 v111, 0x3fb8aa3b, v151
	v_mul_f32_e32 v112, 0xbfb8aa3b, v151
	global_load_dword v151, v38, s[54:55]
	v_exp_f32_e32 v111, v111
	v_exp_f32_e32 v112, v112
	v_mul_f32_e32 v110, v110, v111
	v_mul_f32_e32 v113, v113, v112
	v_sub_f32_e32 v111, 1.0, v111
	v_lshlrev_b32_e32 v112, 16, v162
	global_load_ushort v162, v39, s[38:39]
	v_mul_f32_e32 v111, v111, v113
	v_mul_f32_e32 v112, v110, v112
	v_cvt_pk_bf16_f32 v111, v111, s0
	v_cvt_pk_bf16_f32 v112, v112, s0
	ds_write_b16 v175, v112
	ds_write_b16 v176, v111
	v_mul_f32_e32 v111, 0x3fb8aa3b, v210
	v_mul_f32_e32 v112, 0xbfb8aa3b, v210
	global_load_dword v210, v40, s[54:55]
	v_exp_f32_e32 v111, v111
	v_exp_f32_e32 v112, v112
	v_mul_f32_e32 v110, v110, v111
	v_mul_f32_e32 v113, v113, v112
	v_sub_f32_e32 v111, 1.0, v111
	v_lshlrev_b32_e32 v112, 16, v217
	global_load_ushort v217, v41, s[38:39]
	v_mul_f32_e32 v111, v111, v113
	v_mul_f32_e32 v112, v110, v112
	v_cvt_pk_bf16_f32 v111, v111, s0
	v_cvt_pk_bf16_f32 v112, v112, s0
	ds_write_b16 v177, v112
	ds_write_b16 v178, v111
	v_mul_f32_e32 v111, 0x3fb8aa3b, v220
	v_mul_f32_e32 v112, 0xbfb8aa3b, v220
	global_load_dword v220, v42, s[54:55]
	v_exp_f32_e32 v111, v111
	v_exp_f32_e32 v112, v112
	v_mul_f32_e32 v110, v110, v111
	v_mul_f32_e32 v113, v113, v112
	v_sub_f32_e32 v111, 1.0, v111
	v_lshlrev_b32_e32 v112, 16, v221
	global_load_ushort v221, v43, s[38:39]
	v_mul_f32_e32 v111, v111, v113
	v_mul_f32_e32 v112, v110, v112
	v_cvt_pk_bf16_f32 v111, v111, s0
	v_cvt_pk_bf16_f32 v112, v112, s0
	ds_write_b16 v179, v112
	ds_write_b16 v180, v111
	v_mul_f32_e32 v111, 0x3fb8aa3b, v222
	v_mul_f32_e32 v112, 0xbfb8aa3b, v222
	global_load_dword v222, v44, s[54:55]
	v_exp_f32_e32 v111, v111
	v_exp_f32_e32 v112, v112
	v_mul_f32_e32 v110, v110, v111
	v_mul_f32_e32 v113, v113, v112
	v_sub_f32_e32 v111, 1.0, v111
	v_lshlrev_b32_e32 v112, 16, v223
	global_load_ushort v223, v45, s[38:39]
	v_mul_f32_e32 v111, v111, v113
	v_mul_f32_e32 v112, v110, v112
	v_cvt_pk_bf16_f32 v111, v111, s0
	v_cvt_pk_bf16_f32 v112, v112, s0
	ds_write_b16 v181, v112
	ds_write_b16 v182, v111
	v_mul_f32_e32 v111, 0x3fb8aa3b, v224
	v_mul_f32_e32 v112, 0xbfb8aa3b, v224
	global_load_dword v224, v46, s[54:55]
	v_exp_f32_e32 v111, v111
	v_exp_f32_e32 v112, v112
	v_mul_f32_e32 v110, v110, v111
	v_mul_f32_e32 v113, v113, v112
	v_sub_f32_e32 v111, 1.0, v111
	v_lshlrev_b32_e32 v112, 16, v225
	global_load_ushort v225, v47, s[38:39]
	v_mul_f32_e32 v111, v111, v113
	v_mul_f32_e32 v112, v110, v112
	v_cvt_pk_bf16_f32 v111, v111, s0
	v_cvt_pk_bf16_f32 v112, v112, s0
	ds_write_b16 v183, v112
	ds_write_b16 v184, v111
	v_mul_f32_e32 v111, 0x3fb8aa3b, v226
	v_mul_f32_e32 v112, 0xbfb8aa3b, v226
	global_load_dword v226, v48, s[54:55]
	v_exp_f32_e32 v111, v111
	v_exp_f32_e32 v112, v112
	v_mul_f32_e32 v110, v110, v111
	v_mul_f32_e32 v113, v113, v112
	v_sub_f32_e32 v111, 1.0, v111
	v_lshlrev_b32_e32 v112, 16, v227
	global_load_ushort v227, v49, s[38:39]
	v_mul_f32_e32 v111, v111, v113
	v_mul_f32_e32 v112, v110, v112
	v_cvt_pk_bf16_f32 v111, v111, s0
	v_cvt_pk_bf16_f32 v112, v112, s0
	ds_write_b16 v185, v112
	ds_write_b16 v199, v111
	v_mul_f32_e32 v111, 0x3fb8aa3b, v228
	v_mul_f32_e32 v112, 0xbfb8aa3b, v228
	global_load_dword v228, v50, s[54:55]
	v_exp_f32_e32 v111, v111
	v_exp_f32_e32 v112, v112
	v_mul_f32_e32 v110, v110, v111
	v_mul_f32_e32 v113, v113, v112
	v_sub_f32_e32 v111, 1.0, v111
	v_lshlrev_b32_e32 v112, 16, v229
	global_load_ushort v229, v51, s[38:39]
	v_mul_f32_e32 v111, v111, v113
	v_mul_f32_e32 v112, v110, v112
	v_cvt_pk_bf16_f32 v111, v111, s0
	v_cvt_pk_bf16_f32 v112, v112, s0
	ds_write_b16 v200, v112
	ds_write_b16 v201, v111
	v_mul_f32_e32 v111, 0x3fb8aa3b, v230
	v_mul_f32_e32 v112, 0xbfb8aa3b, v230
	global_load_dword v230, v52, s[54:55]
	v_exp_f32_e32 v111, v111
	v_exp_f32_e32 v112, v112
	v_mul_f32_e32 v110, v110, v111
	v_mul_f32_e32 v113, v113, v112
	v_sub_f32_e32 v111, 1.0, v111
	v_lshlrev_b32_e32 v112, 16, v231
	global_load_ushort v231, v53, s[38:39]
	v_mul_f32_e32 v111, v111, v113
	v_mul_f32_e32 v112, v110, v112
	v_cvt_pk_bf16_f32 v111, v111, s0
	v_cvt_pk_bf16_f32 v112, v112, s0
	ds_write_b16 v202, v112
	ds_write_b16 v203, v111
	v_mul_f32_e32 v111, 0x3fb8aa3b, v232
	v_mul_f32_e32 v112, 0xbfb8aa3b, v232
	global_load_dword v232, v54, s[54:55]
	v_exp_f32_e32 v111, v111
	v_exp_f32_e32 v112, v112
	v_mul_f32_e32 v110, v110, v111
	v_mul_f32_e32 v113, v113, v112
	v_sub_f32_e32 v111, 1.0, v111
	v_lshlrev_b32_e32 v112, 16, v233
	global_load_ushort v233, v55, s[38:39]
	v_mul_f32_e32 v111, v111, v113
	v_mul_f32_e32 v112, v110, v112
	v_cvt_pk_bf16_f32 v111, v111, s0
	v_cvt_pk_bf16_f32 v112, v112, s0
	ds_write_b16 v204, v112
	ds_write_b16 v205, v111
	s_and_saveexec_b64 s[46:47], vcc
	s_cbranch_execz .LBB0_56
	v_add_f32_e32 v72, v72, v73
	v_add_f32_e32 v72, v72, v74
	v_add_f32_e32 v72, v72, v75
	v_mul_f32_e32 v72, 0x3fb8aa3b, v72
	v_exp_f32_e32 v72, v72
	ds_write_b32 v154, v72
